# deferred-rstd norm: row sums stored once per unit (one lane per row/pair), residual loads recycled into dead accumulator registers (all 32 h loads in flight early)
# baseline (speedup 1.0000x reference)
.LBB0_480:
	s_and_b64 vcc, exec, s[12:13]
	s_cbranch_vccnz .Lres_orig
	v_lshrrev_b32_e32 v145, 6, v154
	v_bfe_u32 v146, v163, 5, 2
	v_lshl_add_u32 v151, s22, 2, v146
	v_lshl_add_u32 v145, v145, 2, v146
	v_mul_u32_u24_e32 v145, 2304, v145
	v_add_u32_e32 v145, 135424, v145
	v_and_b32_e32 v146, 15, v189
	v_mul_u32_u24_e32 v146, 144, v146
	v_lshrrev_b32_e32 v147, 4, v189
	v_lshl_add_u32 v146, v147, 5, v146
	v_add_u32_e32 v152, v145, v146
	v_lshrrev_b32_e32 v146, 3, v189
	v_and_b32_e32 v147, 7, v189
	v_mul_u32_u24_e32 v153, 144, v146
	v_lshl_add_u32 v153, v147, 4, v153
	v_add_u32_e32 v153, v145, v153
	v_and_b32_e32 v148, 0xfffffff0, v154
	v_add_u32_e32 v148, v148, v146
	v_lshl_add_u32 v148, s23, 8, v148
	v_and_b32_e32 v149, 0x60, v163
	v_lshl_add_u32 v149, s22, 8, v149
	v_lshlrev_b32_e32 v238, 6, v148
	v_lshl_add_u32 v238, v151, 2, v238
	v_add_u32_e32 v238, 0x4100000, v238
	v_lshl_add_u32 v150, v147, 2, v149
	v_lshlrev_b32_e32 v239, 11, v148
	v_lshl_add_u32 v239, v150, 1, v239
	v_readlane_b32 s18, v254, 27
	v_readlane_b32 s19, v254, 28
	v_readlane_b32 s20, v254, 33
	v_readlane_b32 s21, v254, 34
	v_lshlrev_b32_e32 v150, 2, v150
	s_cmp_eq_u32 s78, 6
	s_cselect_b64 s[40:41], -1, 0
	s_cmp_eq_u32 s78, 2
	s_cselect_b64 vcc, -1, 0
	s_or_b64 s[40:41], s[40:41], vcc
	s_and_b64 vcc, exec, s[40:41]
	s_cselect_b32 s40, s18, s20
	s_cselect_b32 s41, s19, s21
	global_load_dwordx4 v[224:227], v150, s[40:41]
	global_load_dwordx4 v[228:231], v150, s[40:41] offset:512
	v_lshlrev_b32_e32 v148, 12, v148
	v_lshl_add_u32 v149, v149, 2, v148
	v_lshl_add_u32 v144, v147, 4, v149
	s_mov_b32 s38, 0x01010101
	s_mov_b32 s39, 0x01010101
	v_mov_b32_e32 v145, v144
	v_add_u32_e32 v146, 0x8000, v144
	global_load_dwordx4 v[192:195], v145, s[72:73]
	global_load_dwordx4 v[196:199], v146, s[72:73]
	v_add_u32_e32 v147, 0x200, v144
	v_add_u32_e32 v148, 0x8200, v144
	global_load_dwordx4 v[200:203], v147, s[72:73]
	global_load_dwordx4 v[204:207], v148, s[72:73]
	v_add_u32_e32 v145, 0x10000, v144
	v_add_u32_e32 v146, 0x18000, v144
	global_load_dwordx4 v[208:211], v145, s[72:73]
	global_load_dwordx4 v[212:215], v146, s[72:73]
	v_add_u32_e32 v147, 0x10200, v144
	v_add_u32_e32 v148, 0x18200, v144
	global_load_dwordx4 v[216:219], v147, s[72:73]
	global_load_dwordx4 v[220:223], v148, s[72:73]
	ds_write_b128 v152, v[126:129]
	ds_write_b128 v152, v[122:125] offset:16
	ds_read_b128 v[240:243], v153
	ds_read_b128 v[244:247], v153 offset:1152
	ds_write_b128 v152, v[118:121]
	ds_write_b128 v152, v[114:117] offset:16
	ds_read_b128 v[130:133], v153
	ds_read_b128 v[176:179], v153 offset:1152
	s_waitcnt lgkmcnt(4)
	s_waitcnt vmcnt(6)
	v_pk_add_f32 v[240:241], v[240:241], v[192:193]
	v_pk_add_f32 v[242:243], v[242:243], v[194:195]
	v_pk_add_f32 v[244:245], v[244:245], v[196:197]
	v_pk_add_f32 v[246:247], v[246:247], v[198:199]
	v_mov_b32_e32 v180, v144
	v_add_u32_e32 v181, 0x8000, v144
	global_store_dwordx4 v180, v[240:243], s[72:73]
	global_store_dwordx4 v181, v[244:247], s[72:73]
	v_mul_f32_e32 v232, v240, v240
	v_fmac_f32_e32 v232, v241, v241
	v_fmac_f32_e32 v232, v242, v242
	v_fmac_f32_e32 v232, v243, v243
	v_mul_f32_e32 v233, v244, v244
	v_fmac_f32_e32 v233, v245, v245
	v_fmac_f32_e32 v233, v246, v246
	v_fmac_f32_e32 v233, v247, v247
	v_pk_mul_f32 v[248:249], v[240:241], v[224:225]
	v_pk_mul_f32 v[242:243], v[242:243], v[226:227]
	v_cvt_pk_bf16_f32 v234, v248, v249
	v_cvt_pk_bf16_f32 v235, v242, v243
	v_pk_mul_f32 v[248:249], v[244:245], v[224:225]
	v_pk_mul_f32 v[246:247], v[246:247], v[226:227]
	v_cvt_pk_bf16_f32 v236, v248, v249
	v_cvt_pk_bf16_f32 v237, v246, v247
	v_mov_b32_e32 v170, v239
	v_add_u32_e32 v171, 0x4000, v239
	global_store_dwordx2 v170, v[234:235], s[68:69]
	global_store_dwordx2 v171, v[236:237], s[68:69]
	v_add_u32_e32 v145, 0x20000, v144
	v_add_u32_e32 v146, 0x28000, v144
	global_load_dwordx4 v[192:195], v145, s[72:73]
	global_load_dwordx4 v[196:199], v146, s[72:73]
	v_add_u32_e32 v147, 0x20200, v144
	v_add_u32_e32 v148, 0x28200, v144
	global_load_dwordx4 v[126:129], v147, s[72:73]
	global_load_dwordx4 v[122:125], v148, s[72:73]
	ds_write_b128 v152, v[108:111]
	ds_write_b128 v152, v[104:107] offset:16
	ds_read_b128 v[240:243], v153
	ds_read_b128 v[244:247], v153 offset:1152
	s_waitcnt lgkmcnt(4)
	s_waitcnt vmcnt(12)
	v_pk_add_f32 v[130:131], v[130:131], v[200:201]
	v_pk_add_f32 v[132:133], v[132:133], v[202:203]
	v_pk_add_f32 v[176:177], v[176:177], v[204:205]
	v_pk_add_f32 v[178:179], v[178:179], v[206:207]
	v_add_u32_e32 v180, 0x200, v144
	v_add_u32_e32 v181, 0x8200, v144
	global_store_dwordx4 v180, v[130:133], s[72:73]
	global_store_dwordx4 v181, v[176:179], s[72:73]
	v_fmac_f32_e32 v232, v130, v130
	v_fmac_f32_e32 v232, v131, v131
	v_fmac_f32_e32 v232, v132, v132
	v_fmac_f32_e32 v232, v133, v133
	v_fmac_f32_e32 v233, v176, v176
	v_fmac_f32_e32 v233, v177, v177
	v_fmac_f32_e32 v233, v178, v178
	v_fmac_f32_e32 v233, v179, v179
	v_pk_mul_f32 v[248:249], v[130:131], v[228:229]
	v_pk_mul_f32 v[132:133], v[132:133], v[230:231]
	v_cvt_pk_bf16_f32 v234, v248, v249
	v_cvt_pk_bf16_f32 v235, v132, v133
	v_pk_mul_f32 v[248:249], v[176:177], v[228:229]
	v_pk_mul_f32 v[178:179], v[178:179], v[230:231]
	v_cvt_pk_bf16_f32 v236, v248, v249
	v_cvt_pk_bf16_f32 v237, v178, v179
	v_add_u32_e32 v170, 0x100, v239
	v_add_u32_e32 v171, 0x4100, v239
	global_store_dwordx2 v170, v[234:235], s[68:69]
	global_store_dwordx2 v171, v[236:237], s[68:69]
	s_nop 0
	v_add_f32_dpp v232, v232, v232 quad_perm:[1,0,3,2] row_mask:0xf bank_mask:0xf
	v_add_f32_dpp v233, v233, v233 quad_perm:[1,0,3,2] row_mask:0xf bank_mask:0xf
	s_nop 0
	v_add_f32_dpp v232, v232, v232 quad_perm:[2,3,0,1] row_mask:0xf bank_mask:0xf
	v_add_f32_dpp v233, v233, v233 quad_perm:[2,3,0,1] row_mask:0xf bank_mask:0xf
	s_nop 0
	v_add_f32_dpp v232, v232, v232 row_half_mirror row_mask:0xf bank_mask:0xf
	v_add_f32_dpp v233, v233, v233 row_half_mirror row_mask:0xf bank_mask:0xf
	s_nop 0
	v_cndmask_b32_e64 v149, v149, v232, s[38:39]
	v_cndmask_b32_e64 v150, v150, v233, s[38:39]
	v_add_u32_e32 v145, 0x30000, v144
	v_add_u32_e32 v146, 0x38000, v144
	global_load_dwordx4 v[200:203], v145, s[72:73]
	global_load_dwordx4 v[204:207], v146, s[72:73]
	v_add_u32_e32 v147, 0x30200, v144
	v_add_u32_e32 v148, 0x38200, v144
	global_load_dwordx4 v[118:121], v147, s[72:73]
	global_load_dwordx4 v[114:117], v148, s[72:73]
	ds_write_b128 v152, v[100:103]
	ds_write_b128 v152, v[96:99] offset:16
	ds_read_b128 v[130:133], v153
	ds_read_b128 v[176:179], v153 offset:1152
	s_waitcnt lgkmcnt(4)
	s_waitcnt vmcnt(18)
	v_pk_add_f32 v[240:241], v[240:241], v[208:209]
	v_pk_add_f32 v[242:243], v[242:243], v[210:211]
	v_pk_add_f32 v[244:245], v[244:245], v[212:213]
	v_pk_add_f32 v[246:247], v[246:247], v[214:215]
	v_add_u32_e32 v180, 0x10000, v144
	v_add_u32_e32 v181, 0x18000, v144
	global_store_dwordx4 v180, v[240:243], s[72:73]
	global_store_dwordx4 v181, v[244:247], s[72:73]
	v_mul_f32_e32 v232, v240, v240
	v_fmac_f32_e32 v232, v241, v241
	v_fmac_f32_e32 v232, v242, v242
	v_fmac_f32_e32 v232, v243, v243
	v_mul_f32_e32 v233, v244, v244
	v_fmac_f32_e32 v233, v245, v245
	v_fmac_f32_e32 v233, v246, v246
	v_fmac_f32_e32 v233, v247, v247
	v_pk_mul_f32 v[248:249], v[240:241], v[224:225]
	v_pk_mul_f32 v[242:243], v[242:243], v[226:227]
	v_cvt_pk_bf16_f32 v234, v248, v249
	v_cvt_pk_bf16_f32 v235, v242, v243
	v_pk_mul_f32 v[248:249], v[244:245], v[224:225]
	v_pk_mul_f32 v[246:247], v[246:247], v[226:227]
	v_cvt_pk_bf16_f32 v236, v248, v249
	v_cvt_pk_bf16_f32 v237, v246, v247
	v_add_u32_e32 v170, 0x8000, v239
	v_add_u32_e32 v171, 0xc000, v239
	global_store_dwordx2 v170, v[234:235], s[68:69]
	global_store_dwordx2 v171, v[236:237], s[68:69]
	v_add_u32_e32 v145, 0x80000, v144
	v_add_u32_e32 v146, 0x88000, v144
	global_load_dwordx4 v[208:211], v145, s[72:73]
	global_load_dwordx4 v[212:215], v146, s[72:73]
	v_add_u32_e32 v147, 0x80200, v144
	v_add_u32_e32 v148, 0x88200, v144
	global_load_dwordx4 v[108:111], v147, s[72:73]
	global_load_dwordx4 v[104:107], v148, s[72:73]
	ds_write_b128 v152, v[92:95]
	ds_write_b128 v152, v[88:91] offset:16
	ds_read_b128 v[240:243], v153
	ds_read_b128 v[244:247], v153 offset:1152
	s_waitcnt lgkmcnt(4)
	s_waitcnt vmcnt(24)
	v_pk_add_f32 v[130:131], v[130:131], v[216:217]
	v_pk_add_f32 v[132:133], v[132:133], v[218:219]
	v_pk_add_f32 v[176:177], v[176:177], v[220:221]
	v_pk_add_f32 v[178:179], v[178:179], v[222:223]
	v_add_u32_e32 v180, 0x10200, v144
	v_add_u32_e32 v181, 0x18200, v144
	global_store_dwordx4 v180, v[130:133], s[72:73]
	global_store_dwordx4 v181, v[176:179], s[72:73]
	v_fmac_f32_e32 v232, v130, v130
	v_fmac_f32_e32 v232, v131, v131
	v_fmac_f32_e32 v232, v132, v132
	v_fmac_f32_e32 v232, v133, v133
	v_fmac_f32_e32 v233, v176, v176
	v_fmac_f32_e32 v233, v177, v177
	v_fmac_f32_e32 v233, v178, v178
	v_fmac_f32_e32 v233, v179, v179
	v_pk_mul_f32 v[248:249], v[130:131], v[228:229]
	v_pk_mul_f32 v[132:133], v[132:133], v[230:231]
	v_cvt_pk_bf16_f32 v234, v248, v249
	v_cvt_pk_bf16_f32 v235, v132, v133
	v_pk_mul_f32 v[248:249], v[176:177], v[228:229]
	v_pk_mul_f32 v[178:179], v[178:179], v[230:231]
	v_cvt_pk_bf16_f32 v236, v248, v249
	v_cvt_pk_bf16_f32 v237, v178, v179
	v_add_u32_e32 v170, 0x8100, v239
	v_add_u32_e32 v171, 0xc100, v239
	global_store_dwordx2 v170, v[234:235], s[68:69]
	global_store_dwordx2 v171, v[236:237], s[68:69]
	s_nop 0
	v_add_f32_dpp v232, v232, v232 quad_perm:[1,0,3,2] row_mask:0xf bank_mask:0xf
	v_add_f32_dpp v233, v233, v233 quad_perm:[1,0,3,2] row_mask:0xf bank_mask:0xf
	s_nop 0
	v_add_f32_dpp v232, v232, v232 quad_perm:[2,3,0,1] row_mask:0xf bank_mask:0xf
	v_add_f32_dpp v233, v233, v233 quad_perm:[2,3,0,1] row_mask:0xf bank_mask:0xf
	s_nop 0
	v_add_f32_dpp v232, v232, v232 row_half_mirror row_mask:0xf bank_mask:0xf
	v_add_f32_dpp v233, v233, v233 row_half_mirror row_mask:0xf bank_mask:0xf
	s_nop 0
	s_lshl_b64 s[18:19], s[38:39], 1
	v_cndmask_b32_e64 v149, v149, v232, s[18:19]
	v_cndmask_b32_e64 v150, v150, v233, s[18:19]
	v_add_u32_e32 v145, 0x90000, v144
	v_add_u32_e32 v146, 0x98000, v144
	global_load_dwordx4 v[216:219], v145, s[72:73]
	global_load_dwordx4 v[220:223], v146, s[72:73]
	v_add_u32_e32 v147, 0x90200, v144
	v_add_u32_e32 v148, 0x98200, v144
	global_load_dwordx4 v[100:103], v147, s[72:73]
	global_load_dwordx4 v[96:99], v148, s[72:73]
	ds_write_b128 v152, v[84:87]
	ds_write_b128 v152, v[80:83] offset:16
	ds_read_b128 v[130:133], v153
	ds_read_b128 v[176:179], v153 offset:1152
	s_waitcnt lgkmcnt(4)
	s_waitcnt vmcnt(26)
	v_pk_add_f32 v[240:241], v[240:241], v[192:193]
	v_pk_add_f32 v[242:243], v[242:243], v[194:195]
	v_pk_add_f32 v[244:245], v[244:245], v[196:197]
	v_pk_add_f32 v[246:247], v[246:247], v[198:199]
	v_add_u32_e32 v180, 0x20000, v144
	v_add_u32_e32 v181, 0x28000, v144
	global_store_dwordx4 v180, v[240:243], s[72:73]
	global_store_dwordx4 v181, v[244:247], s[72:73]
	v_mul_f32_e32 v232, v240, v240
	v_fmac_f32_e32 v232, v241, v241
	v_fmac_f32_e32 v232, v242, v242
	v_fmac_f32_e32 v232, v243, v243
	v_mul_f32_e32 v233, v244, v244
	v_fmac_f32_e32 v233, v245, v245
	v_fmac_f32_e32 v233, v246, v246
	v_fmac_f32_e32 v233, v247, v247
	v_pk_mul_f32 v[248:249], v[240:241], v[224:225]
	v_pk_mul_f32 v[242:243], v[242:243], v[226:227]
	v_cvt_pk_bf16_f32 v234, v248, v249
	v_cvt_pk_bf16_f32 v235, v242, v243
	v_pk_mul_f32 v[248:249], v[244:245], v[224:225]
	v_pk_mul_f32 v[246:247], v[246:247], v[226:227]
	v_cvt_pk_bf16_f32 v236, v248, v249
	v_cvt_pk_bf16_f32 v237, v246, v247
	v_add_u32_e32 v170, 0x10000, v239
	v_add_u32_e32 v171, 0x14000, v239
	global_store_dwordx2 v170, v[234:235], s[68:69]
	global_store_dwordx2 v171, v[236:237], s[68:69]
	v_add_u32_e32 v145, 0xa0000, v144
	v_add_u32_e32 v146, 0xa8000, v144
	global_load_dwordx4 v[192:195], v145, s[72:73]
	global_load_dwordx4 v[196:199], v146, s[72:73]
	v_add_u32_e32 v147, 0xa0200, v144
	v_add_u32_e32 v148, 0xa8200, v144
	global_load_dwordx4 v[92:95], v147, s[72:73]
	global_load_dwordx4 v[88:91], v148, s[72:73]
	ds_write_b128 v152, v[76:79]
	ds_write_b128 v152, v[72:75] offset:16
	ds_read_b128 v[240:243], v153
	ds_read_b128 v[244:247], v153 offset:1152
	s_waitcnt lgkmcnt(4)
	s_waitcnt vmcnt(32)
	v_pk_add_f32 v[130:131], v[130:131], v[126:127]
	v_pk_add_f32 v[132:133], v[132:133], v[128:129]
	v_pk_add_f32 v[176:177], v[176:177], v[122:123]
	v_pk_add_f32 v[178:179], v[178:179], v[124:125]
	v_add_u32_e32 v180, 0x20200, v144
	v_add_u32_e32 v181, 0x28200, v144
	global_store_dwordx4 v180, v[130:133], s[72:73]
	global_store_dwordx4 v181, v[176:179], s[72:73]
	v_fmac_f32_e32 v232, v130, v130
	v_fmac_f32_e32 v232, v131, v131
	v_fmac_f32_e32 v232, v132, v132
	v_fmac_f32_e32 v232, v133, v133
	v_fmac_f32_e32 v233, v176, v176
	v_fmac_f32_e32 v233, v177, v177
	v_fmac_f32_e32 v233, v178, v178
	v_fmac_f32_e32 v233, v179, v179
	v_pk_mul_f32 v[248:249], v[130:131], v[228:229]
	v_pk_mul_f32 v[132:133], v[132:133], v[230:231]
	v_cvt_pk_bf16_f32 v234, v248, v249
	v_cvt_pk_bf16_f32 v235, v132, v133
	v_pk_mul_f32 v[248:249], v[176:177], v[228:229]
	v_pk_mul_f32 v[178:179], v[178:179], v[230:231]
	v_cvt_pk_bf16_f32 v236, v248, v249
	v_cvt_pk_bf16_f32 v237, v178, v179
	v_add_u32_e32 v170, 0x10100, v239
	v_add_u32_e32 v171, 0x14100, v239
	global_store_dwordx2 v170, v[234:235], s[68:69]
	global_store_dwordx2 v171, v[236:237], s[68:69]
	s_nop 0
	v_add_f32_dpp v232, v232, v232 quad_perm:[1,0,3,2] row_mask:0xf bank_mask:0xf
	v_add_f32_dpp v233, v233, v233 quad_perm:[1,0,3,2] row_mask:0xf bank_mask:0xf
	s_nop 0
	v_add_f32_dpp v232, v232, v232 quad_perm:[2,3,0,1] row_mask:0xf bank_mask:0xf
	v_add_f32_dpp v233, v233, v233 quad_perm:[2,3,0,1] row_mask:0xf bank_mask:0xf
	s_nop 0
	v_add_f32_dpp v232, v232, v232 row_half_mirror row_mask:0xf bank_mask:0xf
	v_add_f32_dpp v233, v233, v233 row_half_mirror row_mask:0xf bank_mask:0xf
	s_nop 0
	s_lshl_b64 s[18:19], s[38:39], 2
	v_cndmask_b32_e64 v149, v149, v232, s[18:19]
	v_cndmask_b32_e64 v150, v150, v233, s[18:19]
	v_add_u32_e32 v145, 0xb0000, v144
	v_add_u32_e32 v146, 0xb8000, v144
	global_load_dwordx4 v[126:129], v145, s[72:73]
	global_load_dwordx4 v[122:125], v146, s[72:73]
	v_add_u32_e32 v147, 0xb0200, v144
	v_add_u32_e32 v148, 0xb8200, v144
	global_load_dwordx4 v[84:87], v147, s[72:73]
	global_load_dwordx4 v[80:83], v148, s[72:73]
	ds_write_b128 v152, v[68:71]
	ds_write_b128 v152, v[64:67] offset:16
	ds_read_b128 v[130:133], v153
	ds_read_b128 v[176:179], v153 offset:1152
	s_waitcnt lgkmcnt(4)
	s_waitcnt vmcnt(34)
	v_pk_add_f32 v[240:241], v[240:241], v[200:201]
	v_pk_add_f32 v[242:243], v[242:243], v[202:203]
	v_pk_add_f32 v[244:245], v[244:245], v[204:205]
	v_pk_add_f32 v[246:247], v[246:247], v[206:207]
	v_add_u32_e32 v180, 0x30000, v144
	v_add_u32_e32 v181, 0x38000, v144
	global_store_dwordx4 v180, v[240:243], s[72:73]
	global_store_dwordx4 v181, v[244:247], s[72:73]
	v_mul_f32_e32 v232, v240, v240
	v_fmac_f32_e32 v232, v241, v241
	v_fmac_f32_e32 v232, v242, v242
	v_fmac_f32_e32 v232, v243, v243
	v_mul_f32_e32 v233, v244, v244
	v_fmac_f32_e32 v233, v245, v245
	v_fmac_f32_e32 v233, v246, v246
	v_fmac_f32_e32 v233, v247, v247
	v_pk_mul_f32 v[248:249], v[240:241], v[224:225]
	v_pk_mul_f32 v[242:243], v[242:243], v[226:227]
	v_cvt_pk_bf16_f32 v234, v248, v249
	v_cvt_pk_bf16_f32 v235, v242, v243
	v_pk_mul_f32 v[248:249], v[244:245], v[224:225]
	v_pk_mul_f32 v[246:247], v[246:247], v[226:227]
	v_cvt_pk_bf16_f32 v236, v248, v249
	v_cvt_pk_bf16_f32 v237, v246, v247
	v_add_u32_e32 v170, 0x18000, v239
	v_add_u32_e32 v171, 0x1c000, v239
	global_store_dwordx2 v170, v[234:235], s[68:69]
	global_store_dwordx2 v171, v[236:237], s[68:69]
	ds_write_b128 v152, v[60:63]
	ds_write_b128 v152, v[56:59] offset:16
	ds_read_b128 v[240:243], v153
	ds_read_b128 v[244:247], v153 offset:1152
	s_waitcnt lgkmcnt(4)
	s_waitcnt vmcnt(36)
	v_pk_add_f32 v[130:131], v[130:131], v[118:119]
	v_pk_add_f32 v[132:133], v[132:133], v[120:121]
	v_pk_add_f32 v[176:177], v[176:177], v[114:115]
	v_pk_add_f32 v[178:179], v[178:179], v[116:117]
	v_add_u32_e32 v180, 0x30200, v144
	v_add_u32_e32 v181, 0x38200, v144
	global_store_dwordx4 v180, v[130:133], s[72:73]
	global_store_dwordx4 v181, v[176:179], s[72:73]
	v_fmac_f32_e32 v232, v130, v130
	v_fmac_f32_e32 v232, v131, v131
	v_fmac_f32_e32 v232, v132, v132
	v_fmac_f32_e32 v232, v133, v133
	v_fmac_f32_e32 v233, v176, v176
	v_fmac_f32_e32 v233, v177, v177
	v_fmac_f32_e32 v233, v178, v178
	v_fmac_f32_e32 v233, v179, v179
	v_pk_mul_f32 v[248:249], v[130:131], v[228:229]
	v_pk_mul_f32 v[132:133], v[132:133], v[230:231]
	v_cvt_pk_bf16_f32 v234, v248, v249
	v_cvt_pk_bf16_f32 v235, v132, v133
	v_pk_mul_f32 v[248:249], v[176:177], v[228:229]
	v_pk_mul_f32 v[178:179], v[178:179], v[230:231]
	v_cvt_pk_bf16_f32 v236, v248, v249
	v_cvt_pk_bf16_f32 v237, v178, v179
	v_add_u32_e32 v170, 0x18100, v239
	v_add_u32_e32 v171, 0x1c100, v239
	global_store_dwordx2 v170, v[234:235], s[68:69]
	global_store_dwordx2 v171, v[236:237], s[68:69]
	s_nop 0
	v_add_f32_dpp v232, v232, v232 quad_perm:[1,0,3,2] row_mask:0xf bank_mask:0xf
	v_add_f32_dpp v233, v233, v233 quad_perm:[1,0,3,2] row_mask:0xf bank_mask:0xf
	s_nop 0
	v_add_f32_dpp v232, v232, v232 quad_perm:[2,3,0,1] row_mask:0xf bank_mask:0xf
	v_add_f32_dpp v233, v233, v233 quad_perm:[2,3,0,1] row_mask:0xf bank_mask:0xf
	s_nop 0
	v_add_f32_dpp v232, v232, v232 row_half_mirror row_mask:0xf bank_mask:0xf
	v_add_f32_dpp v233, v233, v233 row_half_mirror row_mask:0xf bank_mask:0xf
	s_nop 0
	s_lshl_b64 s[18:19], s[38:39], 3
	v_cndmask_b32_e64 v149, v149, v232, s[18:19]
	v_cndmask_b32_e64 v150, v150, v233, s[18:19]
	ds_write_b128 v152, v[52:55]
	ds_write_b128 v152, v[48:51] offset:16
	ds_read_b128 v[130:133], v153
	ds_read_b128 v[176:179], v153 offset:1152
	s_waitcnt lgkmcnt(4)
	s_waitcnt vmcnt(34)
	v_pk_add_f32 v[240:241], v[240:241], v[208:209]
	v_pk_add_f32 v[242:243], v[242:243], v[210:211]
	v_pk_add_f32 v[244:245], v[244:245], v[212:213]
	v_pk_add_f32 v[246:247], v[246:247], v[214:215]
	v_add_u32_e32 v180, 0x80000, v144
	v_add_u32_e32 v181, 0x88000, v144
	global_store_dwordx4 v180, v[240:243], s[72:73]
	global_store_dwordx4 v181, v[244:247], s[72:73]
	v_mul_f32_e32 v232, v240, v240
	v_fmac_f32_e32 v232, v241, v241
	v_fmac_f32_e32 v232, v242, v242
	v_fmac_f32_e32 v232, v243, v243
	v_mul_f32_e32 v233, v244, v244
	v_fmac_f32_e32 v233, v245, v245
	v_fmac_f32_e32 v233, v246, v246
	v_fmac_f32_e32 v233, v247, v247
	v_pk_mul_f32 v[248:249], v[240:241], v[224:225]
	v_pk_mul_f32 v[242:243], v[242:243], v[226:227]
	v_cvt_pk_bf16_f32 v234, v248, v249
	v_cvt_pk_bf16_f32 v235, v242, v243
	v_pk_mul_f32 v[248:249], v[244:245], v[224:225]
	v_pk_mul_f32 v[246:247], v[246:247], v[226:227]
	v_cvt_pk_bf16_f32 v236, v248, v249
	v_cvt_pk_bf16_f32 v237, v246, v247
	v_add_u32_e32 v170, 0x40000, v239
	v_add_u32_e32 v171, 0x44000, v239
	global_store_dwordx2 v170, v[234:235], s[68:69]
	global_store_dwordx2 v171, v[236:237], s[68:69]
	ds_write_b128 v152, v[44:47]
	ds_write_b128 v152, v[40:43] offset:16
	ds_read_b128 v[240:243], v153
	ds_read_b128 v[244:247], v153 offset:1152
	s_waitcnt lgkmcnt(4)
	s_waitcnt vmcnt(36)
	v_pk_add_f32 v[130:131], v[130:131], v[108:109]
	v_pk_add_f32 v[132:133], v[132:133], v[110:111]
	v_pk_add_f32 v[176:177], v[176:177], v[104:105]
	v_pk_add_f32 v[178:179], v[178:179], v[106:107]
	v_add_u32_e32 v180, 0x80200, v144
	v_add_u32_e32 v181, 0x88200, v144
	global_store_dwordx4 v180, v[130:133], s[72:73]
	global_store_dwordx4 v181, v[176:179], s[72:73]
	v_fmac_f32_e32 v232, v130, v130
	v_fmac_f32_e32 v232, v131, v131
	v_fmac_f32_e32 v232, v132, v132
	v_fmac_f32_e32 v232, v133, v133
	v_fmac_f32_e32 v233, v176, v176
	v_fmac_f32_e32 v233, v177, v177
	v_fmac_f32_e32 v233, v178, v178
	v_fmac_f32_e32 v233, v179, v179
	v_pk_mul_f32 v[248:249], v[130:131], v[228:229]
	v_pk_mul_f32 v[132:133], v[132:133], v[230:231]
	v_cvt_pk_bf16_f32 v234, v248, v249
	v_cvt_pk_bf16_f32 v235, v132, v133
	v_pk_mul_f32 v[248:249], v[176:177], v[228:229]
	v_pk_mul_f32 v[178:179], v[178:179], v[230:231]
	v_cvt_pk_bf16_f32 v236, v248, v249
	v_cvt_pk_bf16_f32 v237, v178, v179
	v_add_u32_e32 v170, 0x40100, v239
	v_add_u32_e32 v171, 0x44100, v239
	global_store_dwordx2 v170, v[234:235], s[68:69]
	global_store_dwordx2 v171, v[236:237], s[68:69]
	s_nop 0
	v_add_f32_dpp v232, v232, v232 quad_perm:[1,0,3,2] row_mask:0xf bank_mask:0xf
	v_add_f32_dpp v233, v233, v233 quad_perm:[1,0,3,2] row_mask:0xf bank_mask:0xf
	s_nop 0
	v_add_f32_dpp v232, v232, v232 quad_perm:[2,3,0,1] row_mask:0xf bank_mask:0xf
	v_add_f32_dpp v233, v233, v233 quad_perm:[2,3,0,1] row_mask:0xf bank_mask:0xf
	s_nop 0
	v_add_f32_dpp v232, v232, v232 row_half_mirror row_mask:0xf bank_mask:0xf
	v_add_f32_dpp v233, v233, v233 row_half_mirror row_mask:0xf bank_mask:0xf
	s_nop 0
	s_lshl_b64 s[18:19], s[38:39], 4
	v_cndmask_b32_e64 v149, v149, v232, s[18:19]
	v_cndmask_b32_e64 v150, v150, v233, s[18:19]
	ds_write_b128 v152, v[36:39]
	ds_write_b128 v152, v[32:35] offset:16
	ds_read_b128 v[130:133], v153
	ds_read_b128 v[176:179], v153 offset:1152
	s_waitcnt lgkmcnt(4)
	s_waitcnt vmcnt(34)
	v_pk_add_f32 v[240:241], v[240:241], v[216:217]
	v_pk_add_f32 v[242:243], v[242:243], v[218:219]
	v_pk_add_f32 v[244:245], v[244:245], v[220:221]
	v_pk_add_f32 v[246:247], v[246:247], v[222:223]
	v_add_u32_e32 v180, 0x90000, v144
	v_add_u32_e32 v181, 0x98000, v144
	global_store_dwordx4 v180, v[240:243], s[72:73]
	global_store_dwordx4 v181, v[244:247], s[72:73]
	v_mul_f32_e32 v232, v240, v240
	v_fmac_f32_e32 v232, v241, v241
	v_fmac_f32_e32 v232, v242, v242
	v_fmac_f32_e32 v232, v243, v243
	v_mul_f32_e32 v233, v244, v244
	v_fmac_f32_e32 v233, v245, v245
	v_fmac_f32_e32 v233, v246, v246
	v_fmac_f32_e32 v233, v247, v247
	v_pk_mul_f32 v[248:249], v[240:241], v[224:225]
	v_pk_mul_f32 v[242:243], v[242:243], v[226:227]
	v_cvt_pk_bf16_f32 v234, v248, v249
	v_cvt_pk_bf16_f32 v235, v242, v243
	v_pk_mul_f32 v[248:249], v[244:245], v[224:225]
	v_pk_mul_f32 v[246:247], v[246:247], v[226:227]
	v_cvt_pk_bf16_f32 v236, v248, v249
	v_cvt_pk_bf16_f32 v237, v246, v247
	v_add_u32_e32 v170, 0x48000, v239
	v_add_u32_e32 v171, 0x4c000, v239
	global_store_dwordx2 v170, v[234:235], s[68:69]
	global_store_dwordx2 v171, v[236:237], s[68:69]
	ds_write_b128 v152, v[28:31]
	ds_write_b128 v152, v[24:27] offset:16
	ds_read_b128 v[240:243], v153
	ds_read_b128 v[244:247], v153 offset:1152
	s_waitcnt lgkmcnt(4)
	s_waitcnt vmcnt(36)
	v_pk_add_f32 v[130:131], v[130:131], v[100:101]
	v_pk_add_f32 v[132:133], v[132:133], v[102:103]
	v_pk_add_f32 v[176:177], v[176:177], v[96:97]
	v_pk_add_f32 v[178:179], v[178:179], v[98:99]
	v_add_u32_e32 v180, 0x90200, v144
	v_add_u32_e32 v181, 0x98200, v144
	global_store_dwordx4 v180, v[130:133], s[72:73]
	global_store_dwordx4 v181, v[176:179], s[72:73]
	v_fmac_f32_e32 v232, v130, v130
	v_fmac_f32_e32 v232, v131, v131
	v_fmac_f32_e32 v232, v132, v132
	v_fmac_f32_e32 v232, v133, v133
	v_fmac_f32_e32 v233, v176, v176
	v_fmac_f32_e32 v233, v177, v177
	v_fmac_f32_e32 v233, v178, v178
	v_fmac_f32_e32 v233, v179, v179
	v_pk_mul_f32 v[248:249], v[130:131], v[228:229]
	v_pk_mul_f32 v[132:133], v[132:133], v[230:231]
	v_cvt_pk_bf16_f32 v234, v248, v249
	v_cvt_pk_bf16_f32 v235, v132, v133
	v_pk_mul_f32 v[248:249], v[176:177], v[228:229]
	v_pk_mul_f32 v[178:179], v[178:179], v[230:231]
	v_cvt_pk_bf16_f32 v236, v248, v249
	v_cvt_pk_bf16_f32 v237, v178, v179
	v_add_u32_e32 v170, 0x48100, v239
	v_add_u32_e32 v171, 0x4c100, v239
	global_store_dwordx2 v170, v[234:235], s[68:69]
	global_store_dwordx2 v171, v[236:237], s[68:69]
	s_nop 0
	v_add_f32_dpp v232, v232, v232 quad_perm:[1,0,3,2] row_mask:0xf bank_mask:0xf
	v_add_f32_dpp v233, v233, v233 quad_perm:[1,0,3,2] row_mask:0xf bank_mask:0xf
	s_nop 0
	v_add_f32_dpp v232, v232, v232 quad_perm:[2,3,0,1] row_mask:0xf bank_mask:0xf
	v_add_f32_dpp v233, v233, v233 quad_perm:[2,3,0,1] row_mask:0xf bank_mask:0xf
	s_nop 0
	v_add_f32_dpp v232, v232, v232 row_half_mirror row_mask:0xf bank_mask:0xf
	v_add_f32_dpp v233, v233, v233 row_half_mirror row_mask:0xf bank_mask:0xf
	s_nop 0
	s_lshl_b64 s[18:19], s[38:39], 5
	v_cndmask_b32_e64 v149, v149, v232, s[18:19]
	v_cndmask_b32_e64 v150, v150, v233, s[18:19]
	ds_write_b128 v152, v[20:23]
	ds_write_b128 v152, v[16:19] offset:16
	ds_read_b128 v[130:133], v153
	ds_read_b128 v[176:179], v153 offset:1152
	s_waitcnt lgkmcnt(4)
	s_waitcnt vmcnt(34)
	v_pk_add_f32 v[240:241], v[240:241], v[192:193]
	v_pk_add_f32 v[242:243], v[242:243], v[194:195]
	v_pk_add_f32 v[244:245], v[244:245], v[196:197]
	v_pk_add_f32 v[246:247], v[246:247], v[198:199]
	v_add_u32_e32 v180, 0xa0000, v144
	v_add_u32_e32 v181, 0xa8000, v144
	global_store_dwordx4 v180, v[240:243], s[72:73]
	global_store_dwordx4 v181, v[244:247], s[72:73]
	v_mul_f32_e32 v232, v240, v240
	v_fmac_f32_e32 v232, v241, v241
	v_fmac_f32_e32 v232, v242, v242
	v_fmac_f32_e32 v232, v243, v243
	v_mul_f32_e32 v233, v244, v244
	v_fmac_f32_e32 v233, v245, v245
	v_fmac_f32_e32 v233, v246, v246
	v_fmac_f32_e32 v233, v247, v247
	v_pk_mul_f32 v[248:249], v[240:241], v[224:225]
	v_pk_mul_f32 v[242:243], v[242:243], v[226:227]
	v_cvt_pk_bf16_f32 v234, v248, v249
	v_cvt_pk_bf16_f32 v235, v242, v243
	v_pk_mul_f32 v[248:249], v[244:245], v[224:225]
	v_pk_mul_f32 v[246:247], v[246:247], v[226:227]
	v_cvt_pk_bf16_f32 v236, v248, v249
	v_cvt_pk_bf16_f32 v237, v246, v247
	v_add_u32_e32 v170, 0x50000, v239
	v_add_u32_e32 v171, 0x54000, v239
	global_store_dwordx2 v170, v[234:235], s[68:69]
	global_store_dwordx2 v171, v[236:237], s[68:69]
	ds_write_b128 v152, v[12:15]
	ds_write_b128 v152, v[8:11] offset:16
	ds_read_b128 v[240:243], v153
	ds_read_b128 v[244:247], v153 offset:1152
	s_waitcnt lgkmcnt(4)
	s_waitcnt vmcnt(36)
	v_pk_add_f32 v[130:131], v[130:131], v[92:93]
	v_pk_add_f32 v[132:133], v[132:133], v[94:95]
	v_pk_add_f32 v[176:177], v[176:177], v[88:89]
	v_pk_add_f32 v[178:179], v[178:179], v[90:91]
	v_add_u32_e32 v180, 0xa0200, v144
	v_add_u32_e32 v181, 0xa8200, v144
	global_store_dwordx4 v180, v[130:133], s[72:73]
	global_store_dwordx4 v181, v[176:179], s[72:73]
	v_fmac_f32_e32 v232, v130, v130
	v_fmac_f32_e32 v232, v131, v131
	v_fmac_f32_e32 v232, v132, v132
	v_fmac_f32_e32 v232, v133, v133
	v_fmac_f32_e32 v233, v176, v176
	v_fmac_f32_e32 v233, v177, v177
	v_fmac_f32_e32 v233, v178, v178
	v_fmac_f32_e32 v233, v179, v179
	v_pk_mul_f32 v[248:249], v[130:131], v[228:229]
	v_pk_mul_f32 v[132:133], v[132:133], v[230:231]
	v_cvt_pk_bf16_f32 v234, v248, v249
	v_cvt_pk_bf16_f32 v235, v132, v133
	v_pk_mul_f32 v[248:249], v[176:177], v[228:229]
	v_pk_mul_f32 v[178:179], v[178:179], v[230:231]
	v_cvt_pk_bf16_f32 v236, v248, v249
	v_cvt_pk_bf16_f32 v237, v178, v179
	v_add_u32_e32 v170, 0x50100, v239
	v_add_u32_e32 v171, 0x54100, v239
	global_store_dwordx2 v170, v[234:235], s[68:69]
	global_store_dwordx2 v171, v[236:237], s[68:69]
	s_nop 0
	v_add_f32_dpp v232, v232, v232 quad_perm:[1,0,3,2] row_mask:0xf bank_mask:0xf
	v_add_f32_dpp v233, v233, v233 quad_perm:[1,0,3,2] row_mask:0xf bank_mask:0xf
	s_nop 0
	v_add_f32_dpp v232, v232, v232 quad_perm:[2,3,0,1] row_mask:0xf bank_mask:0xf
	v_add_f32_dpp v233, v233, v233 quad_perm:[2,3,0,1] row_mask:0xf bank_mask:0xf
	s_nop 0
	v_add_f32_dpp v232, v232, v232 row_half_mirror row_mask:0xf bank_mask:0xf
	v_add_f32_dpp v233, v233, v233 row_half_mirror row_mask:0xf bank_mask:0xf
	s_nop 0
	s_lshl_b64 s[18:19], s[38:39], 6
	v_cndmask_b32_e64 v149, v149, v232, s[18:19]
	v_cndmask_b32_e64 v150, v150, v233, s[18:19]
	ds_write_b128 v152, v[4:7]
	ds_write_b128 v152, v[0:3] offset:16
	ds_read_b128 v[130:133], v153
	ds_read_b128 v[176:179], v153 offset:1152
	s_waitcnt lgkmcnt(4)
	s_waitcnt vmcnt(34)
	v_pk_add_f32 v[240:241], v[240:241], v[126:127]
	v_pk_add_f32 v[242:243], v[242:243], v[128:129]
	v_pk_add_f32 v[244:245], v[244:245], v[122:123]
	v_pk_add_f32 v[246:247], v[246:247], v[124:125]
	v_add_u32_e32 v180, 0xb0000, v144
	v_add_u32_e32 v181, 0xb8000, v144
	global_store_dwordx4 v180, v[240:243], s[72:73]
	global_store_dwordx4 v181, v[244:247], s[72:73]
	v_mul_f32_e32 v232, v240, v240
	v_fmac_f32_e32 v232, v241, v241
	v_fmac_f32_e32 v232, v242, v242
	v_fmac_f32_e32 v232, v243, v243
	v_mul_f32_e32 v233, v244, v244
	v_fmac_f32_e32 v233, v245, v245
	v_fmac_f32_e32 v233, v246, v246
	v_fmac_f32_e32 v233, v247, v247
	v_pk_mul_f32 v[248:249], v[240:241], v[224:225]
	v_pk_mul_f32 v[242:243], v[242:243], v[226:227]
	v_cvt_pk_bf16_f32 v234, v248, v249
	v_cvt_pk_bf16_f32 v235, v242, v243
	v_pk_mul_f32 v[248:249], v[244:245], v[224:225]
	v_pk_mul_f32 v[246:247], v[246:247], v[226:227]
	v_cvt_pk_bf16_f32 v236, v248, v249
	v_cvt_pk_bf16_f32 v237, v246, v247
	v_add_u32_e32 v170, 0x58000, v239
	v_add_u32_e32 v171, 0x5c000, v239
	global_store_dwordx2 v170, v[234:235], s[68:69]
	global_store_dwordx2 v171, v[236:237], s[68:69]
	s_waitcnt lgkmcnt(0)
	s_waitcnt vmcnt(36)
	v_pk_add_f32 v[130:131], v[130:131], v[84:85]
	v_pk_add_f32 v[132:133], v[132:133], v[86:87]
	v_pk_add_f32 v[176:177], v[176:177], v[80:81]
	v_pk_add_f32 v[178:179], v[178:179], v[82:83]
	v_add_u32_e32 v180, 0xb0200, v144
	v_add_u32_e32 v181, 0xb8200, v144
	global_store_dwordx4 v180, v[130:133], s[72:73]
	global_store_dwordx4 v181, v[176:179], s[72:73]
	v_fmac_f32_e32 v232, v130, v130
	v_fmac_f32_e32 v232, v131, v131
	v_fmac_f32_e32 v232, v132, v132
	v_fmac_f32_e32 v232, v133, v133
	v_fmac_f32_e32 v233, v176, v176
	v_fmac_f32_e32 v233, v177, v177
	v_fmac_f32_e32 v233, v178, v178
	v_fmac_f32_e32 v233, v179, v179
	v_pk_mul_f32 v[248:249], v[130:131], v[228:229]
	v_pk_mul_f32 v[132:133], v[132:133], v[230:231]
	v_cvt_pk_bf16_f32 v234, v248, v249
	v_cvt_pk_bf16_f32 v235, v132, v133
	v_pk_mul_f32 v[248:249], v[176:177], v[228:229]
	v_pk_mul_f32 v[178:179], v[178:179], v[230:231]
	v_cvt_pk_bf16_f32 v236, v248, v249
	v_cvt_pk_bf16_f32 v237, v178, v179
	v_add_u32_e32 v170, 0x58100, v239
	v_add_u32_e32 v171, 0x5c100, v239
	global_store_dwordx2 v170, v[234:235], s[68:69]
	global_store_dwordx2 v171, v[236:237], s[68:69]
	s_nop 0
	v_add_f32_dpp v232, v232, v232 quad_perm:[1,0,3,2] row_mask:0xf bank_mask:0xf
	v_add_f32_dpp v233, v233, v233 quad_perm:[1,0,3,2] row_mask:0xf bank_mask:0xf
	s_nop 0
	v_add_f32_dpp v232, v232, v232 quad_perm:[2,3,0,1] row_mask:0xf bank_mask:0xf
	v_add_f32_dpp v233, v233, v233 quad_perm:[2,3,0,1] row_mask:0xf bank_mask:0xf
	s_nop 0
	v_add_f32_dpp v232, v232, v232 row_half_mirror row_mask:0xf bank_mask:0xf
	v_add_f32_dpp v233, v233, v233 row_half_mirror row_mask:0xf bank_mask:0xf
	s_nop 0
	s_lshl_b64 s[18:19], s[38:39], 7
	v_cndmask_b32_e64 v149, v149, v232, s[18:19]
	v_cndmask_b32_e64 v150, v150, v233, s[18:19]
	v_and_b32_e32 v145, 7, v189
	v_lshrrev_b32_e32 v146, 2, v145
	v_and_b32_e32 v145, 3, v145
	v_lshlrev_b32_e32 v146, 13, v146
	v_lshl_add_u32 v145, v145, 10, v146
	v_add_u32_e32 v145, v145, v238
	global_store_dword v145, v149, s[68:69]
	global_store_dword v145, v150, s[68:69] offset:512
	s_branch .Lres_join
